# loop-edge edit 3: rescale test and rare rescale block moved in front of the step barriers (per-wave scratch only); post-barrier path is the next MFMA / one branch
# speedup vs baseline: 1.0028x; 1.0028x over previous
.LBB0_833:
	s_waitcnt lgkmcnt(6)
	v_mfma_f32_32x32x16_bf16 v[48:63], v[180:183], v[6:9], v[48:63]
	v_exp_f32_e32 v128, v128
	v_exp_f32_e32 v129, v129
	v_exp_f32_e32 v130, v130
	v_exp_f32_e32 v131, v131
	ds_read_b64_tr_b16 v[6:7], v14 offset:51200
	ds_read_b64_tr_b16 v[8:9], v14 offset:51712
	s_waitcnt lgkmcnt(6)
	v_mfma_f32_32x32x16_bf16 v[32:47], v[180:183], v[10:13], v[32:47]
	v_exp_f32_e32 v132, v132
	v_exp_f32_e32 v133, v133
	v_exp_f32_e32 v134, v134
	v_exp_f32_e32 v135, v135
	ds_read_b64_tr_b16 v[10:11], v14 offset:55296
	ds_read_b64_tr_b16 v[12:13], v14 offset:55808
	s_waitcnt lgkmcnt(6)
	v_mfma_f32_32x32x16_bf16 v[48:63], v[172:175], v[80:83], v[48:63]
	v_exp_f32_e32 v136, v136
	v_exp_f32_e32 v137, v137
	v_exp_f32_e32 v138, v138
	v_exp_f32_e32 v139, v139
	ds_read_b64_tr_b16 v[80:81], v14 offset:52224
	ds_read_b64_tr_b16 v[82:83], v14 offset:52736
	s_waitcnt lgkmcnt(6)
	v_mfma_f32_32x32x16_bf16 v[32:47], v[172:175], v[2:5], v[32:47]
	v_exp_f32_e32 v140, v140
	v_exp_f32_e32 v141, v141
	v_exp_f32_e32 v142, v142
	v_exp_f32_e32 v143, v143
	v_add_u32_e32 v15, s12, v214
	ds_read_b64_tr_b16 v[84:85], v14 offset:56320
	ds_read_b64_tr_b16 v[86:87], v14 offset:56832
	ds_read_b128 v[2:5], v15
	s_waitcnt lgkmcnt(7)
	v_mfma_f32_32x32x16_bf16 v[48:63], v[160:163], v[6:9], v[48:63]
	v_exp_f32_e32 v112, v112
	v_exp_f32_e32 v113, v113
	v_exp_f32_e32 v114, v114
	v_exp_f32_e32 v115, v115
	ds_read_b128 v[6:9], v15 offset:512
	s_waitcnt lgkmcnt(6)
	v_mfma_f32_32x32x16_bf16 v[32:47], v[160:163], v[10:13], v[32:47]
	v_exp_f32_e32 v116, v116
	v_exp_f32_e32 v117, v117
	v_exp_f32_e32 v118, v118
	v_exp_f32_e32 v119, v119
	ds_read_b128 v[10:13], v15 offset:2048
	s_waitcnt lgkmcnt(5)
	v_mfma_f32_32x32x16_bf16 v[48:63], v[152:155], v[80:83], v[48:63]
	v_exp_f32_e32 v120, v120
	v_exp_f32_e32 v121, v121
	v_exp_f32_e32 v122, v122
	v_exp_f32_e32 v123, v123
	ds_read_b128 v[184:187], v15 offset:2560
	s_waitcnt lgkmcnt(4)
	v_mfma_f32_32x32x16_bf16 v[32:47], v[152:155], v[84:87], v[32:47]
	v_exp_f32_e32 v124, v124
	v_exp_f32_e32 v125, v125
	v_exp_f32_e32 v126, v126
	v_exp_f32_e32 v127, v127
	s_add_i32 s12, s23, 0x2000
	s_cmpk_lg_i32 s23, 0x4000
	s_cselect_b32 s12, s12, 0
	s_andn2_b64 vcc, exec, s[62:63]
	s_cbranch_vccz .Latt_rA
.Latt_rA_ret:
	s_waitcnt vmcnt(3) lgkmcnt(4)
	s_barrier

.LBB0_836:
	s_waitcnt lgkmcnt(6)
	v_mfma_f32_32x32x16_bf16 v[48:63], v[180:183], v[112:115], v[48:63]
	v_exp_f32_e32 v96, v96
	v_exp_f32_e32 v97, v97
	v_exp_f32_e32 v98, v98
	v_exp_f32_e32 v99, v99
	ds_read_b64_tr_b16 v[112:113], v14 offset:51200
	ds_read_b64_tr_b16 v[114:115], v14 offset:51712
	s_waitcnt lgkmcnt(6)
	v_mfma_f32_32x32x16_bf16 v[32:47], v[180:183], v[10:13], v[32:47]
	v_exp_f32_e32 v100, v100
	v_exp_f32_e32 v101, v101
	v_exp_f32_e32 v102, v102
	v_exp_f32_e32 v103, v103
	ds_read_b64_tr_b16 v[10:11], v14 offset:55296
	ds_read_b64_tr_b16 v[12:13], v14 offset:55808
	s_waitcnt lgkmcnt(6)
	v_mfma_f32_32x32x16_bf16 v[48:63], v[172:175], v[6:9], v[48:63]
	v_exp_f32_e32 v104, v104
	v_exp_f32_e32 v105, v105
	v_exp_f32_e32 v106, v106
	v_exp_f32_e32 v107, v107
	ds_read_b64_tr_b16 v[6:7], v14 offset:52224
	ds_read_b64_tr_b16 v[8:9], v14 offset:52736
	s_waitcnt lgkmcnt(6)
	v_mfma_f32_32x32x16_bf16 v[32:47], v[172:175], v[2:5], v[32:47]
	v_exp_f32_e32 v108, v108
	v_exp_f32_e32 v109, v109
	v_exp_f32_e32 v110, v110
	v_exp_f32_e32 v111, v111
	v_add_u32_e32 v0, s22, v214
	ds_read_b64_tr_b16 v[2:3], v14 offset:56320
	ds_read_b64_tr_b16 v[4:5], v14 offset:56832
	ds_read_b128 v[196:199], v0
	s_waitcnt lgkmcnt(7)
	v_mfma_f32_32x32x16_bf16 v[48:63], v[160:163], v[112:115], v[48:63]
	v_exp_f32_e32 v80, v80
	v_exp_f32_e32 v81, v81
	v_exp_f32_e32 v82, v82
	v_exp_f32_e32 v83, v83
	ds_read_b128 v[184:187], v0 offset:512
	s_waitcnt lgkmcnt(6)
	v_mfma_f32_32x32x16_bf16 v[32:47], v[160:163], v[10:13], v[32:47]
	v_exp_f32_e32 v84, v84
	v_exp_f32_e32 v85, v85
	v_exp_f32_e32 v86, v86
	v_exp_f32_e32 v87, v87
	ds_read_b128 v[188:191], v0 offset:2048
	s_waitcnt lgkmcnt(5)
	v_mfma_f32_32x32x16_bf16 v[48:63], v[152:155], v[6:9], v[48:63]
	v_exp_f32_e32 v88, v88
	v_exp_f32_e32 v89, v89
	v_exp_f32_e32 v90, v90
	v_exp_f32_e32 v91, v91
	ds_read_b128 v[192:195], v0 offset:2560
	s_waitcnt lgkmcnt(4)
	v_mfma_f32_32x32x16_bf16 v[32:47], v[152:155], v[2:5], v[32:47]
	v_exp_f32_e32 v92, v92
	v_exp_f32_e32 v93, v93
	v_exp_f32_e32 v94, v94
	v_exp_f32_e32 v95, v95
	s_add_i32 s22, s12, 0x2000
	s_cmpk_lg_i32 s12, 0x4000
	s_cselect_b32 s22, s22, 0
	s_add_u32 s60, s60, 0x2000
	s_addc_u32 s61, s61, 0
	s_add_u32 s58, s58, 0x20000
	s_addc_u32 s59, s59, 0
	s_add_i32 s67, s67, 2
	s_add_u32 s6, s6, 0x20000
	s_addc_u32 s7, s7, 0
	s_cmp_ge_i32 s10, s66
	s_cbranch_scc1 .Latt_mx
	s_mov_b32 s101, s23
	s_mov_b32 s10, s12
	s_mov_b32 s23, s22
	s_andn2_b64 vcc, exec, s[62:63]
	s_cbranch_vccz .Latt_rB
.Latt_rB_ret:
	s_waitcnt vmcnt(3) lgkmcnt(4)
	s_barrier
	s_branch .LBB0_832

.Latt_rB:
	s_waitcnt lgkmcnt(0)
	ds_read_b128 v[2:5], v207 offset:96
	ds_read_b128 v[6:9], v207 offset:64
	ds_read_b128 v[10:13], v207 offset:32
	ds_read_b128 v[112:115], v207
	s_waitcnt lgkmcnt(3)
	v_pk_mul_f32 v[62:63], v[62:63], v[4:5]
	s_waitcnt lgkmcnt(2)
	v_pk_mul_f32 v[58:59], v[58:59], v[8:9]
	s_waitcnt lgkmcnt(1)
	v_pk_mul_f32 v[54:55], v[54:55], v[12:13]
	s_waitcnt lgkmcnt(0)
	v_pk_mul_f32 v[50:51], v[50:51], v[114:115]
	v_pk_mul_f32 v[60:61], v[60:61], v[2:3]
	v_pk_mul_f32 v[56:57], v[56:57], v[6:7]
	v_pk_mul_f32 v[52:53], v[52:53], v[10:11]
	v_pk_mul_f32 v[48:49], v[48:49], v[112:113]
	v_pk_mul_f32 v[46:47], v[46:47], v[4:5]
	v_pk_mul_f32 v[42:43], v[42:43], v[8:9]
	v_pk_mul_f32 v[38:39], v[38:39], v[12:13]
	v_pk_mul_f32 v[34:35], v[34:35], v[114:115]
	v_pk_mul_f32 v[44:45], v[44:45], v[2:3]
	v_pk_mul_f32 v[40:41], v[40:41], v[6:7]
	v_pk_mul_f32 v[36:37], v[36:37], v[10:11]
	v_pk_mul_f32 v[32:33], v[32:33], v[112:113]
	s_branch .Latt_rB_ret
